# phase 0: replaced the 10 per-matrix serialized f32->bf16 transpose tile loops by one hand-written generic loop, two tiles in flight (register double buffer), k-pair packed LDS transposition, one barri
# speedup vs baseline: 1.0039x; 1.0039x over previous
; __device__ __forceinline__ int bid_fresh() { int t = blockIdx.x; asm volatile("" : "+s"(t)); return t; }
; __device__ __forceinline__ void phase0(PP p, unsigned char* shm) {
;     unsigned char* ws = p->ws;
;     float* tile = (float*)shm;
;     constexpr int C_IN = 32 * 14, C_OUT = 32 * 8, C_XQ = 32 * 2, C_XO = 8 * 8, C_UP = 32 * 32, C_DN = 128 * 8, C_GLU = 8 * 2, C_POOL = 16, C_PW = 8 * 2;
;     constexpr int C_LAYER = C_IN + C_OUT + 3 * C_XQ + C_XO + C_UP + C_DN + C_GLU + C_POOL + C_PW;
;     for (int it = bid_fresh(); it < DEPTH * C_LAYER; it += gridDim.x) {
;         const int l = it / C_LAYER; int r = it % C_LAYER;
;         if (r < C_IN) { tconv_tile_w(p->in[5] + (size_t)l * D * INW, INW, r / 14, r % 14, (bf16_t*)(ws + WS_WIN) + (size_t)l * INW * D, D, tile, p->in[4] + (size_t)l * D); continue; } r -= C_IN;
;         if (r < C_OUT) { tconv_tile_w(p->in[23] + (size_t)l * D * D, D, r / 8, r % 8, (bf16_t*)(ws + WS_WOUT) + (size_t)l * D * D, D, tile, p->in[22] + (size_t)l * D); continue; } r -= C_OUT;
;         if (r < C_XQ) { tconv_tile_w(p->in[25] + (size_t)l * D * 512, 512, r / 2, r % 2, (bf16_t*)(ws + WS_WXQ) + (size_t)l * 512 * D, D, tile, p->in[24] + (size_t)l * D); continue; } r -= C_XQ;
;         if (r < C_XQ) { tconv_tile_w(p->in[26] + (size_t)l * D * 512, 512, r / 2, r % 2, (bf16_t*)(ws + WS_WKV) + (size_t)(l * 1024) * D, D, tile); continue; } r -= C_XQ;
;         if (r < C_XQ) { tconv_tile_w(p->in[27] + (size_t)l * D * 512, 512, r / 2, r % 2, (bf16_t*)(ws + WS_WKV) + (size_t)(l * 1024 + 512) * D, D, tile); continue; } r -= C_XQ;
;         if (r < C_XO) { tconv_tile_w(p->in[28] + (size_t)l * 512 * D, D, r / 8, r % 8, (bf16_t*)(ws + WS_WXO) + (size_t)l * D * 512, 512, tile); continue; } r -= C_XO;
;         if (r < C_UP) { tconv_tile_w(p->in[30] + (size_t)l * D * DFF, DFF, r / 32, r % 32, (bf16_t*)(ws + WS_WUP) + (size_t)l * DFF * D, D, tile, p->in[29] + (size_t)l * D); continue; } r -= C_UP;
;         if (r < C_DN) { if (l == 0) tconv_tile_w(p->in[31] + (size_t)l * DFF * D, D, r / 8, r % 8, (bf16_t*)(ws + WS_WDN) + (size_t)l * D * DFF, DFF, tile); continue; } r -= C_DN;
;         bf16_t* wsm = (bf16_t*)(ws + WS_WSM) + (size_t)l * 1536 * 512;
;         if (r < C_GLU) { tconv_tile_w(p->in[14] + (size_t)l * 512 * 512, 512, r / 2, r % 2, wsm, 512, tile); continue; } r -= C_GLU;
.LBB0_17:
	s_mov_b64 s[14:15], s[0:1]
	s_load_dwordx2 s[12:13], s[14:15], 0x110
	v_writelane_b32 v254, s26, 2
	s_cmpk_gt_i32 s26, 0x2fbf
	s_cbranch_scc1 .LBB0_71
	s_waitcnt lgkmcnt(0)
	v_and_b32_e32 v96, 63, v222
	v_lshlrev_b32_e32 v96, 4, v96
	v_lshrrev_b32_e32 v113, 6, v222
	v_and_b32_e32 v107, 7, v222
	v_readfirstlane_b32 s53, v113
	v_lshrrev_b32_e32 v108, 3, v222
	v_mul_u32_u24_e32 v106, 0x1010, v107
	v_lshl_add_u32 v106, v108, 2, v106
	v_lshlrev_b32_e32 v107, 4, v107
	s_lshl_b32 s54, s53, 3
	s_mul_i32 s2, s53, 0x1010
	v_add_u32_e32 v114, s2, v96
	v_add_u32_e32 v115, 0x404, v114
	v_add_u32_e32 v116, 0x808, v114
	v_add_u32_e32 v117, 0xc0c, v114
	v_add_u32_e32 v118, 0x8100, v114
	v_add_u32_e32 v119, 0x8100, v115
	v_add_u32_e32 v120, 0x8100, v116
	v_add_u32_e32 v121, 0x8100, v117
	s_mov_b32 s27, 0
	s_mov_b32 s28, 0
	s_mov_b32 s29, s26
	s_mov_b32 s60, 1
	s_mov_b32 s42, 0
	s_mov_b32 s30, 448
	s_mov_b32 s62, 1
.Ltc_ft_2:
	s_cmp_lt_u32 s29, s30
	s_cbranch_scc1 .Ltc_ff_1
	s_sub_u32 s29, s29, s30
	s_add_u32 s28, s28, 1
	s_cmp_eq_u32 s28, 0
	s_cbranch_scc0 .Ltc_c0_4
	s_mov_b32 s30, 448
	s_branch .Ltc_cdone0_3
.Ltc_c0_4:
	s_cmp_eq_u32 s28, 1
	s_cbranch_scc0 .Ltc_c0_5
	s_mov_b32 s30, 256
	s_branch .Ltc_cdone0_3
.Ltc_c0_5:
	s_cmp_eq_u32 s28, 2
	s_cbranch_scc0 .Ltc_c0_6
	s_mov_b32 s30, 64
	s_branch .Ltc_cdone0_3
.Ltc_c0_6:
	s_cmp_eq_u32 s28, 3
	s_cbranch_scc0 .Ltc_c0_7
	s_mov_b32 s30, 64
	s_branch .Ltc_cdone0_3
.Ltc_c0_7:
	s_cmp_eq_u32 s28, 4
	s_cbranch_scc0 .Ltc_c0_8
	s_mov_b32 s30, 64
	s_branch .Ltc_cdone0_3
.Ltc_c0_8:
	s_cmp_eq_u32 s28, 5
	s_cbranch_scc0 .Ltc_c0_9
	s_mov_b32 s30, 64
	s_branch .Ltc_cdone0_3
.Ltc_c0_9:
	s_cmp_eq_u32 s28, 6
	s_cbranch_scc0 .Ltc_c0_10
	s_mov_b32 s30, 1024
	s_branch .Ltc_cdone0_3
.Ltc_c0_10:
	s_cmp_eq_u32 s28, 7
	s_cbranch_scc0 .Ltc_c0_11
	s_mov_b32 s30, 1024
	s_branch .Ltc_cdone0_3
.Ltc_c0_11:
	s_cmp_eq_u32 s28, 8
	s_cbranch_scc0 .Ltc_c0_12
	s_mov_b32 s30, 16
	s_branch .Ltc_cdone0_3
.Ltc_c0_12:
	s_mov_b32 s30, 16

; __device__ __forceinline__ void tconv_tile_w(const float* src, int N, int kb, int nb, bf16_t* dst, int ldd, float* tile, const float* kscale = nullptr) {
; __device__ __forceinline__ void phase0(PP p, unsigned char* shm) {
;     ...
;     for (int it = bid_fresh(); it < DEPTH * C_LAYER; it += gridDim.x) {
;         const int l = it / C_LAYER; int r = it % C_LAYER;
;         if (r < C_IN) { tconv_tile_w(p->in[5] + (size_t)l * D * INW, INW, r / 14, r % 14, (bf16_t*)(ws + WS_WIN) + (size_t)l * INW * D, D, tile, p->in[4] + (size_t)l * D); continue; } r -= C_IN;
;         if (r < C_OUT) { tconv_tile_w(p->in[23] + (size_t)l * D * D, D, r / 8, r % 8, (bf16_t*)(ws + WS_WOUT) + (size_t)l * D * D, D, tile, p->in[22] + (size_t)l * D); continue; } r -= C_OUT;
;         if (r < C_XQ) { tconv_tile_w(p->in[25] + (size_t)l * D * 512, 512, r / 2, r % 2, (bf16_t*)(ws + WS_WXQ) + (size_t)l * 512 * D, D, tile, p->in[24] + (size_t)l * D); continue; } r -= C_XQ;
;         if (r < C_XQ) { tconv_tile_w(p->in[26] + (size_t)l * D * 512, 512, r / 2, r % 2, (bf16_t*)(ws + WS_WKV) + (size_t)(l * 1024) * D, D, tile); continue; } r -= C_XQ;
;         if (r < C_XQ) { tconv_tile_w(p->in[27] + (size_t)l * D * 512, 512, r / 2, r % 2, (bf16_t*)(ws + WS_WKV) + (size_t)(l * 1024 + 512) * D, D, tile); continue; } r -= C_XQ;
;         if (r < C_XO) { tconv_tile_w(p->in[28] + (size_t)l * 512 * D, D, r / 8, r % 8, (bf16_t*)(ws + WS_WXO) + (size_t)l * D * 512, 512, tile); continue; } r -= C_XO;
;         if (r < C_UP) { tconv_tile_w(p->in[30] + (size_t)l * D * DFF, DFF, r / 32, r % 32, (bf16_t*)(ws + WS_WUP) + (size_t)l * DFF * D, D, tile, p->in[29] + (size_t)l * D); continue; } r -= C_UP;
;         if (r < C_DN) { if (l == 0) tconv_tile_w(p->in[31] + (size_t)l * DFF * D, D, r / 8, r % 8, (bf16_t*)(ws + WS_WDN) + (size_t)l * D * DFF, DFF, tile); continue; } r -= C_DN;
;         bf16_t* wsm = (bf16_t*)(ws + WS_WSM) + (size_t)l * 1536 * 512;
;         if (r < C_GLU) { tconv_tile_w(p->in[14] + (size_t)l * 512 * 512, 512, r / 2, r % 2, wsm, 512, tile); continue; } r -= C_GLU;
;         if (r < C_POOL) { const int gi = r >> 2, q = r & 3; tconv_tile(p->in[15] + (size_t)(l * 4 + gi) * 128 * 128, 128, q >> 1, q & 1, wsm + (size_t)(512 + gi * 128) * 512 + gi * 128, 512, tile); continue; } r -= C_POOL;
;         tconv_tile_w(p->in[21] + (size_t)l * 512 * 512, 512, r / 2, r % 2, wsm + (size_t)1024 * 512, 512, tile);
.Ltc_ff_1:
	s_cmp_eq_u32 s28, 0
	s_cbranch_scc0 .Ltc_k_15
	s_mov_b32 s30, 448
	s_mov_b32 s55, 0x28
	s_mov_b32 s34, 0x3800
	s_mov_b32 s31, 0x124a
	s_mov_b32 s33, 14
	s_mov_b32 s35, 0x1000
	s_mov_b32 s56, 0x0
	s_mov_b32 s57, 0xe00000
	s_mov_b32 s58, 0x1c00000
	s_mov_b32 s42, 0x20
	s_branch .Ltc_segdone_14
.Ltc_k_15:
	s_cmp_eq_u32 s28, 1
	s_cbranch_scc0 .Ltc_k_16
	s_mov_b32 s30, 256
	s_mov_b32 s55, 0xb8
	s_mov_b32 s34, 0x2000
	s_mov_b32 s31, 0x2000
	s_mov_b32 s33, 8
	s_mov_b32 s35, 0x1000
	s_mov_b32 s56, 0x3800000
	s_mov_b32 s57, 0x800000
	s_mov_b32 s58, 0x1000000
	s_mov_b32 s42, 0xb0
	s_branch .Ltc_segdone_14
.Ltc_k_16:
	s_cmp_eq_u32 s28, 2
	s_cbranch_scc0 .Ltc_k_17
	s_mov_b32 s30, 64
	s_mov_b32 s55, 0xc8
	s_mov_b32 s34, 0x800
	s_mov_b32 s31, 0x8000
	s_mov_b32 s33, 2
	s_mov_b32 s35, 0x1000
	s_mov_b32 s56, 0x5800000
	s_mov_b32 s57, 0x200000
	s_mov_b32 s58, 0x400000
	s_mov_b32 s42, 0xc0
	s_branch .Ltc_segdone_14
.Ltc_k_17:
	s_cmp_eq_u32 s28, 3
	s_cbranch_scc0 .Ltc_k_18
	s_mov_b32 s30, 64
	s_mov_b32 s55, 0xd0
	s_mov_b32 s34, 0x800
	s_mov_b32 s31, 0x8000
	s_mov_b32 s33, 2
	s_mov_b32 s35, 0x1000
	s_mov_b32 s56, 0x6000000
	s_mov_b32 s57, 0x400000
	s_mov_b32 s58, 0x400000
	s_mov_b32 s42, 0x0
	s_branch .Ltc_segdone_14
.Ltc_k_18:
	s_cmp_eq_u32 s28, 4
	s_cbranch_scc0 .Ltc_k_19
	s_mov_b32 s30, 64
	s_mov_b32 s55, 0xd8
	s_mov_b32 s34, 0x800
	s_mov_b32 s31, 0x8000
	s_mov_b32 s33, 2
	s_mov_b32 s35, 0x1000
	s_mov_b32 s56, 0x6200000
	s_mov_b32 s57, 0x400000
	s_mov_b32 s58, 0x400000
	s_mov_b32 s42, 0x0
	s_branch .Ltc_segdone_14
.Ltc_k_19:
	s_cmp_eq_u32 s28, 5
	s_cbranch_scc0 .Ltc_k_20
	s_mov_b32 s30, 64
	s_mov_b32 s55, 0xe0
	s_mov_b32 s34, 0x2000
	s_mov_b32 s31, 0x2000
	s_mov_b32 s33, 8
	s_mov_b32 s35, 0x400
	s_mov_b32 s56, 0x7000000
	s_mov_b32 s57, 0x200000
	s_mov_b32 s58, 0x400000
	s_mov_b32 s42, 0x0
	s_branch .Ltc_segdone_14
.Ltc_k_20:
	s_cmp_eq_u32 s28, 6
	s_cbranch_scc0 .Ltc_k_21
	s_mov_b32 s30, 1024
	s_mov_b32 s55, 0xf0
	s_mov_b32 s34, 0x8000
	s_mov_b32 s31, 0x800
	s_mov_b32 s33, 32
	s_mov_b32 s35, 0x1000
	s_mov_b32 s56, 0x7800000
	s_mov_b32 s57, 0x2000000
	s_mov_b32 s58, 0x4000000
	s_mov_b32 s42, 0xe8
	s_branch .Ltc_segdone_14
.Ltc_k_21:
	s_cmp_eq_u32 s28, 7
	s_cbranch_scc0 .Ltc_k_22
	s_mov_b32 s30, 1024
	s_mov_b32 s55, 0xf8
	s_mov_b32 s34, 0x2000
	s_mov_b32 s31, 0x2000
	s_mov_b32 s33, 8
	s_mov_b32 s35, 0x4000
	s_mov_b32 s56, 0xf800000
	s_mov_b32 s57, 0x2000000
	s_mov_b32 s58, 0x4000000
	s_mov_b32 s42, 0x0
	s_branch .Ltc_segdone_14
.Ltc_k_22:
	s_cmp_eq_u32 s28, 8
	s_cbranch_scc0 .Ltc_k_23
	s_mov_b32 s30, 16
	s_mov_b32 s55, 0x70
	s_mov_b32 s34, 0x800
	s_mov_b32 s31, 0x8000
	s_mov_b32 s33, 2
	s_mov_b32 s35, 0x400
	s_mov_b32 s56, 0x17800000
	s_mov_b32 s57, 0x180000
	s_mov_b32 s58, 0x100000
	s_mov_b32 s42, 0x0
	s_branch .Ltc_segdone_14
.Ltc_k_23:
	s_mov_b32 s30, 16
	s_mov_b32 s55, 0xa8
	s_mov_b32 s34, 0x800
	s_mov_b32 s31, 0x8000
	s_mov_b32 s33, 2
	s_mov_b32 s35, 0x400
	s_mov_b32 s56, 0x17900000
	s_mov_b32 s57, 0x180000
	s_mov_b32 s58, 0x100000
	s_mov_b32 s42, 0x0
.Ltc_segdone_14:
	s_load_dwordx2 s[36:37], s[14:15], s55
	s_cmp_eq_u32 s42, 0
	s_cbranch_scc1 .Ltc_nosc_25
	s_load_dwordx2 s[40:41], s[14:15], s42
.Ltc_nosc_25:
	s_mul_i32 s2, s27, s58
	s_mul_i32 s3, s27, s57
	s_add_u32 s38, s12, s56
	s_addc_u32 s39, s13, 0
	s_add_u32 s38, s38, s3
	s_addc_u32 s39, s39, 0
	s_waitcnt lgkmcnt(0)
	s_add_u32 s36, s36, s2
	s_addc_u32 s37, s37, 0
	s_lshl_b32 s2, s27, 13
	s_add_u32 s40, s40, s2
	s_addc_u32 s41, s41, 0
	s_mul_i32 s2, s29, s31
	s_lshr_b32 s2, s2, 16
	s_mul_i32 s3, s2, s33
	s_sub_u32 s3, s29, s3
	s_lshl_b32 s4, s2, 6
	s_add_u32 s4, s4, s54
	s_mul_i32 s5, s4, s34
	s_lshl_b32 s6, s3, 10
	s_add_u32 s5, s5, s6
	s_add_u32 s44, s36, s5
	s_addc_u32 s45, s37, 0
	s_lshl_b32 s6, s3, 8
	s_mul_i32 s6, s6, s35
	s_lshl_b32 s7, s2, 7
	s_add_u32 s6, s6, s7
	s_add_u32 s46, s38, s6
	s_addc_u32 s47, s39, 0
	s_mov_b32 s48, s35
	s_mov_b32 s49, s34
	s_mov_b32 s61, s42
	s_cmp_eq_u32 s42, 0
	s_cbranch_scc1 .Ltc_tnosc_26
	s_lshl_b32 s4, s4, 2
	s_load_dwordx8 s[76:83], s[40:41], s4
.Ltc_tnosc_26:
	s_mov_b32 s43, 1
	v_mad_u32_u24 v97, s49, 0, v96
	v_mad_u32_u24 v98, s49, 1, v96
	v_mad_u32_u24 v99, s49, 2, v96
	v_mad_u32_u24 v100, s49, 3, v96
	v_mad_u32_u24 v101, s49, 4, v96
	v_mad_u32_u24 v102, s49, 5, v96
	v_mad_u32_u24 v103, s49, 6, v96
	v_mad_u32_u24 v104, s49, 7, v96
	global_load_dwordx4 v[0:3], v97, s[44:45] nt
	global_load_dwordx4 v[4:7], v98, s[44:45] nt
	global_load_dwordx4 v[8:11], v99, s[44:45] nt
	global_load_dwordx4 v[12:15], v100, s[44:45] nt
	global_load_dwordx4 v[16:19], v101, s[44:45] nt
	global_load_dwordx4 v[20:23], v102, s[44:45] nt
	global_load_dwordx4 v[24:27], v103, s[44:45] nt
	global_load_dwordx4 v[28:31], v104, s[44:45] nt
	s_waitcnt lgkmcnt(0)
	s_mov_b64 s[50:51], s[46:47]
	s_mov_b32 s52, s48
	s_mov_b32 s59, s61
	s_mov_b64 s[68:69], s[76:77]
	s_mov_b64 s[70:71], s[78:79]
	s_mov_b64 s[72:73], s[80:81]
	s_mov_b64 s[74:75], s[82:83]
.Ltc_loop_27:
	s_add_u32 s29, s29, s66
	s_mov_b32 s62, 0
.Ltc_adv_29:
	s_cmp_lt_u32 s29, s30
	s_cbranch_scc1 .Ltc_found_30
	s_sub_u32 s29, s29, s30
	s_add_u32 s28, s28, 1
	s_mov_b32 s62, 1
	s_cmp_eq_u32 s28, 7
	s_cbranch_scc0 .Ltc_nodn_33
	s_cmp_eq_u32 s27, 0
	s_cbranch_scc1 .Ltc_nodn_33
	s_mov_b32 s28, 8
.Ltc_nodn_33:
	s_cmp_eq_u32 s28, 10
	s_cbranch_scc0 .Ltc_nowrap_34
	s_mov_b32 s28, 0
	s_add_u32 s27, s27, 1
	s_cmp_eq_u32 s27, 4
	s_cbranch_scc1 .Ltc_none_31
.Ltc_nowrap_34:
	s_cmp_eq_u32 s28, 0
	s_cbranch_scc0 .Ltc_c_37
	s_mov_b32 s30, 448
	s_branch .Ltc_cdone_36

; __device__ __forceinline__ int bid_fresh() { int t = blockIdx.x; asm volatile("" : "+s"(t)); return t; }
; __device__ __forceinline__ void phase0(PP p, unsigned char* shm) {
;     ...
;     for (int it = bid_fresh(); it < DEPTH * C_LAYER; it += gridDim.x) {
;         const int l = it / C_LAYER; int r = it % C_LAYER;
;         if (r < C_IN) { tconv_tile_w(p->in[5] + (size_t)l * D * INW, INW, r / 14, r % 14, (bf16_t*)(ws + WS_WIN) + (size_t)l * INW * D, D, tile, p->in[4] + (size_t)l * D); continue; } r -= C_IN;
;         if (r < C_OUT) { tconv_tile_w(p->in[23] + (size_t)l * D * D, D, r / 8, r % 8, (bf16_t*)(ws + WS_WOUT) + (size_t)l * D * D, D, tile, p->in[22] + (size_t)l * D); continue; } r -= C_OUT;
;         if (r < C_XQ) { tconv_tile_w(p->in[25] + (size_t)l * D * 512, 512, r / 2, r % 2, (bf16_t*)(ws + WS_WXQ) + (size_t)l * 512 * D, D, tile, p->in[24] + (size_t)l * D); continue; } r -= C_XQ;
;         if (r < C_XQ) { tconv_tile_w(p->in[26] + (size_t)l * D * 512, 512, r / 2, r % 2, (bf16_t*)(ws + WS_WKV) + (size_t)(l * 1024) * D, D, tile); continue; } r -= C_XQ;
;         if (r < C_XQ) { tconv_tile_w(p->in[27] + (size_t)l * D * 512, 512, r / 2, r % 2, (bf16_t*)(ws + WS_WKV) + (size_t)(l * 1024 + 512) * D, D, tile); continue; } r -= C_XQ;
;         if (r < C_XO) { tconv_tile_w(p->in[28] + (size_t)l * 512 * D, D, r / 8, r % 8, (bf16_t*)(ws + WS_WXO) + (size_t)l * D * 512, 512, tile); continue; } r -= C_XO;
;         if (r < C_UP) { tconv_tile_w(p->in[30] + (size_t)l * D * DFF, DFF, r / 32, r % 32, (bf16_t*)(ws + WS_WUP) + (size_t)l * DFF * D, D, tile, p->in[29] + (size_t)l * D); continue; } r -= C_UP;
;         if (r < C_DN) { if (l == 0) tconv_tile_w(p->in[31] + (size_t)l * DFF * D, D, r / 8, r % 8, (bf16_t*)(ws + WS_WDN) + (size_t)l * D * DFF, DFF, tile); continue; } r -= C_DN;
;         bf16_t* wsm = (bf16_t*)(ws + WS_WSM) + (size_t)l * 1536 * 512;
;         if (r < C_GLU) { tconv_tile_w(p->in[14] + (size_t)l * 512 * 512, 512, r / 2, r % 2, wsm, 512, tile); continue; } r -= C_GLU;
;         if (r < C_POOL) { const int gi = r >> 2, q = r & 3; tconv_tile(p->in[15] + (size_t)(l * 4 + gi) * 128 * 128, 128, q >> 1, q & 1, wsm + (size_t)(512 + gi * 128) * 512 + gi * 128, 512, tile); continue; } r -= C_POOL;
;         tconv_tile_w(p->in[21] + (size_t)l * 512 * 512, 512, r / 2, r % 2, wsm + (size_t)1024 * 512, 512, tile);
.Ltc_found_30:
	s_cmp_eq_u32 s62, 0
	s_cbranch_scc1 .Ltc_noseg_35
	s_cmp_eq_u32 s28, 0
	s_cbranch_scc0 .Ltc_k_48
	s_mov_b32 s30, 448
	s_mov_b32 s55, 0x28
	s_mov_b32 s34, 0x3800
	s_mov_b32 s31, 0x124a
	s_mov_b32 s33, 14
	s_mov_b32 s35, 0x1000
	s_mov_b32 s56, 0x0
	s_mov_b32 s57, 0xe00000
	s_mov_b32 s58, 0x1c00000
	s_mov_b32 s42, 0x20
	s_branch .Ltc_segdone_47

; __device__ __forceinline__ void tconv_tile_w(const float* src, int N, int kb, int nb, bf16_t* dst, int ldd, float* tile, const float* kscale = nullptr) {
;     ...
;     for (int p = 0; p < 8; ++p) { const int idx = tid + 512 * p, r = idx >> 6, c4 = idx & 63;
;         v[p] = __builtin_nontemporal_load((const f32x4*)(src + (size_t)(kb * 64 + r) * N + nb * 256 + c4 * 4)); }
;     if (kscale) {
; #pragma unroll
;         for (int p = 0; p < 8; ++p) v[p] = v[p] * kscale[kb * 64 + ((tid + 512 * p) >> 6)];
;     }
; #pragma unroll
;     for (int p = 0; p < 8; ++p) { const int idx = tid + 512 * p, r = idx >> 6, c4 = idx & 63;
;         float* t = tile + r * 257 + c4 * 4; t[0] = v[p][0]; t[1] = v[p][1]; t[2] = v[p][2]; t[3] = v[p][3]; }
;     __syncthreads();
; #pragma unroll
;     for (int q = 0; q < 4; ++q) { const int id = tid + 512 * q, n = id >> 3, k8 = id & 7;
;         const float* s = tile + (k8 * 8) * 257 + n;
;         u32x4 o; o.x = pk2(s[0], s[257]); o.y = pk2(s[2 * 257], s[3 * 257]); o.z = pk2(s[4 * 257], s[5 * 257]); o.w = pk2(s[6 * 257], s[7 * 257]);
;         *(u32x4*)(dst + (size_t)(nb * 256 + n) * ldd + kb * 64 + k8 * 8) = o; }
;     __syncthreads();
; __device__ __forceinline__ void phase0(PP p, unsigned char* shm) {
;     ...
;     for (int it = bid_fresh(); it < DEPTH * C_LAYER; it += gridDim.x) {
;         const int l = it / C_LAYER; int r = it % C_LAYER;
;         if (r < C_IN) { tconv_tile_w(p->in[5] + (size_t)l * D * INW, INW, r / 14, r % 14, (bf16_t*)(ws + WS_WIN) + (size_t)l * INW * D, D, tile, p->in[4] + (size_t)l * D); continue; } r -= C_IN;
;         if (r < C_OUT) { tconv_tile_w(p->in[23] + (size_t)l * D * D, D, r / 8, r % 8, (bf16_t*)(ws + WS_WOUT) + (size_t)l * D * D, D, tile, p->in[22] + (size_t)l * D); continue; } r -= C_OUT;
;         if (r < C_XQ) { tconv_tile_w(p->in[25] + (size_t)l * D * 512, 512, r / 2, r % 2, (bf16_t*)(ws + WS_WXQ) + (size_t)l * 512 * D, D, tile, p->in[24] + (size_t)l * D); continue; } r -= C_XQ;
;         if (r < C_XQ) { tconv_tile_w(p->in[26] + (size_t)l * D * 512, 512, r / 2, r % 2, (bf16_t*)(ws + WS_WKV) + (size_t)(l * 1024) * D, D, tile); continue; } r -= C_XQ;
;         if (r < C_XQ) { tconv_tile_w(p->in[27] + (size_t)l * D * 512, 512, r / 2, r % 2, (bf16_t*)(ws + WS_WKV) + (size_t)(l * 1024 + 512) * D, D, tile); continue; } r -= C_XQ;
.Ltc_nosc_58:
	s_mul_i32 s2, s27, s58
	s_mul_i32 s3, s27, s57
	s_add_u32 s38, s12, s56
	s_addc_u32 s39, s13, 0
	s_add_u32 s38, s38, s3
	s_addc_u32 s39, s39, 0
	s_waitcnt lgkmcnt(0)
	s_add_u32 s36, s36, s2
	s_addc_u32 s37, s37, 0
	s_lshl_b32 s2, s27, 13
	s_add_u32 s40, s40, s2
	s_addc_u32 s41, s41, 0
.Ltc_noseg_35:
	s_mul_i32 s2, s29, s31
	s_lshr_b32 s2, s2, 16
	s_mul_i32 s3, s2, s33
	s_sub_u32 s3, s29, s3
	s_lshl_b32 s4, s2, 6
	s_add_u32 s4, s4, s54
	s_mul_i32 s5, s4, s34
	s_lshl_b32 s6, s3, 10
	s_add_u32 s5, s5, s6
	s_add_u32 s44, s36, s5
	s_addc_u32 s45, s37, 0
	s_lshl_b32 s6, s3, 8
	s_mul_i32 s6, s6, s35
	s_lshl_b32 s7, s2, 7
	s_add_u32 s6, s6, s7
	s_add_u32 s46, s38, s6
	s_addc_u32 s47, s39, 0
	s_mov_b32 s48, s35
	s_mov_b32 s49, s34
	s_mov_b32 s61, s42
	s_cmp_eq_u32 s42, 0
	s_cbranch_scc1 .Ltc_tnosc_59
	s_lshl_b32 s4, s4, 2
	s_load_dwordx8 s[76:83], s[40:41], s4
.Ltc_tnosc_59:
	s_mov_b32 s43, 1
	s_branch .Ltc_advend_32
.Ltc_none_31:
	s_mov_b32 s43, 0
.Ltc_advend_32:
	s_cmp_eq_u32 s43, 0
	s_cbranch_scc1 .Ltc_skipA_60
	v_mad_u32_u24 v97, s49, 0, v96
	v_mad_u32_u24 v98, s49, 1, v96
	v_mad_u32_u24 v99, s49, 2, v96
	v_mad_u32_u24 v100, s49, 3, v96
	v_mad_u32_u24 v101, s49, 4, v96
	v_mad_u32_u24 v102, s49, 5, v96
	v_mad_u32_u24 v103, s49, 6, v96
	v_mad_u32_u24 v104, s49, 7, v96
	global_load_dwordx4 v[32:35], v97, s[44:45] nt
	global_load_dwordx4 v[36:39], v98, s[44:45] nt
	global_load_dwordx4 v[40:43], v99, s[44:45] nt
	global_load_dwordx4 v[44:47], v100, s[44:45] nt
	global_load_dwordx4 v[48:51], v101, s[44:45] nt
	global_load_dwordx4 v[52:55], v102, s[44:45] nt
	global_load_dwordx4 v[56:59], v103, s[44:45] nt
	global_load_dwordx4 v[60:63], v104, s[44:45] nt
.Ltc_skipA_60:
	s_cmp_eq_u32 s43, 0
	s_cbranch_scc1 .Ltc_wlast_63
	s_cmp_eq_u32 s60, 0
	s_cbranch_scc1 .Ltc_w12_61
	s_waitcnt vmcnt(8)
	s_branch .Ltc_wd_62
.Ltc_w12_61:
	s_waitcnt vmcnt(12)
	s_branch .Ltc_wd_62
.Ltc_wlast_63:
	s_waitcnt vmcnt(4)
	s_cmp_eq_u32 s60, 0
	s_cbranch_scc1 .Ltc_wd_62
	s_waitcnt vmcnt(0)
.Ltc_wd_62:
	s_mov_b32 s60, 0
	s_cmp_eq_u32 s59, 0
	s_cbranch_scc1 .Ltc_pnosc_64
	v_mul_f32_e32 v0, s68, v0
	v_mul_f32_e32 v1, s68, v1
	v_mul_f32_e32 v2, s68, v2
	v_mul_f32_e32 v3, s68, v3
	v_mul_f32_e32 v4, s69, v4
	v_mul_f32_e32 v5, s69, v5
	v_mul_f32_e32 v6, s69, v6
	v_mul_f32_e32 v7, s69, v7
	v_mul_f32_e32 v8, s70, v8
	v_mul_f32_e32 v9, s70, v9
	v_mul_f32_e32 v10, s70, v10
	v_mul_f32_e32 v11, s70, v11
	v_mul_f32_e32 v12, s71, v12
	v_mul_f32_e32 v13, s71, v13
	v_mul_f32_e32 v14, s71, v14
	v_mul_f32_e32 v15, s71, v15
	v_mul_f32_e32 v16, s72, v16
	v_mul_f32_e32 v17, s72, v17
	v_mul_f32_e32 v18, s72, v18
	v_mul_f32_e32 v19, s72, v19
	v_mul_f32_e32 v20, s73, v20
	v_mul_f32_e32 v21, s73, v21
	v_mul_f32_e32 v22, s73, v22
	v_mul_f32_e32 v23, s73, v23
	v_mul_f32_e32 v24, s74, v24
	v_mul_f32_e32 v25, s74, v25
	v_mul_f32_e32 v26, s74, v26
	v_mul_f32_e32 v27, s74, v27
	v_mul_f32_e32 v28, s75, v28
	v_mul_f32_e32 v29, s75, v29
	v_mul_f32_e32 v30, s75, v30
	v_mul_f32_e32 v31, s75, v31
.Ltc_pnosc_64:
	v_cvt_pk_bf16_f32 v64, v0, v4
	v_cvt_pk_bf16_f32 v65, v1, v5
	v_cvt_pk_bf16_f32 v66, v2, v6
	v_cvt_pk_bf16_f32 v67, v3, v7
	v_cvt_pk_bf16_f32 v68, v8, v12
	v_cvt_pk_bf16_f32 v69, v9, v13
	v_cvt_pk_bf16_f32 v70, v10, v14
	v_cvt_pk_bf16_f32 v71, v11, v15
	v_cvt_pk_bf16_f32 v72, v16, v20
	v_cvt_pk_bf16_f32 v73, v17, v21
	v_cvt_pk_bf16_f32 v74, v18, v22
	v_cvt_pk_bf16_f32 v75, v19, v23
	v_cvt_pk_bf16_f32 v76, v24, v28
	v_cvt_pk_bf16_f32 v77, v25, v29
	v_cvt_pk_bf16_f32 v78, v26, v30
	v_cvt_pk_bf16_f32 v79, v27, v31
	ds_write2_b32 v114, v64, v65 offset1:1
	ds_write2_b32 v114, v66, v67 offset0:2 offset1:3
	ds_write2_b32 v115, v68, v69 offset1:1
	ds_write2_b32 v115, v70, v71 offset0:2 offset1:3
	ds_write2_b32 v116, v72, v73 offset1:1
	ds_write2_b32 v116, v74, v75 offset0:2 offset1:3
	ds_write2_b32 v117, v76, v77 offset1:1
	ds_write2_b32 v117, v78, v79 offset0:2 offset1:3
	v_add_u32_e32 v113, 0, v108
	v_mad_u32_u24 v109, v113, s52, v107
	v_add_u32_e32 v113, 64, v108
	v_mad_u32_u24 v110, v113, s52, v107
	v_add_u32_e32 v113, 128, v108
	v_mad_u32_u24 v111, v113, s52, v107
	v_add_u32_e32 v113, 192, v108
	v_mad_u32_u24 v112, v113, s52, v107
	s_waitcnt lgkmcnt(0)
	s_barrier
	ds_read_b32 v80, v106 offset:0
	ds_read_b32 v81, v106 offset:1028
	ds_read_b32 v82, v106 offset:2056
	ds_read_b32 v83, v106 offset:3084
	ds_read_b32 v84, v106 offset:256
	ds_read_b32 v85, v106 offset:1284
	ds_read_b32 v86, v106 offset:2312
	ds_read_b32 v87, v106 offset:3340
	ds_read_b32 v88, v106 offset:512
	ds_read_b32 v89, v106 offset:1540
	ds_read_b32 v90, v106 offset:2568
	ds_read_b32 v91, v106 offset:3596
	ds_read_b32 v92, v106 offset:768
	ds_read_b32 v93, v106 offset:1796
	ds_read_b32 v94, v106 offset:2824
	ds_read_b32 v95, v106 offset:3852
	s_waitcnt lgkmcnt(12)
	global_store_dwordx4 v109, v[80:83], s[50:51]
	s_waitcnt lgkmcnt(8)
	global_store_dwordx4 v110, v[84:87], s[50:51]
	s_waitcnt lgkmcnt(4)
	global_store_dwordx4 v111, v[88:91], s[50:51]
	s_waitcnt lgkmcnt(0)
	global_store_dwordx4 v112, v[92:95], s[50:51]
	s_cmp_eq_u32 s43, 0
	s_cbranch_scc1 .Ltc_exit_28
	s_waitcnt lgkmcnt(0)
	s_mov_b64 s[50:51], s[46:47]
	s_mov_b32 s52, s48
	s_mov_b32 s59, s61
	s_mov_b64 s[68:69], s[76:77]
	s_mov_b64 s[70:71], s[78:79]
	s_mov_b64 s[72:73], s[80:81]
	s_mov_b64 s[74:75], s[82:83]
	s_add_u32 s29, s29, s66
	s_mov_b32 s62, 0

; __device__ __forceinline__ void tconv_tile_w(const float* src, int N, int kb, int nb, bf16_t* dst, int ldd, float* tile, const float* kscale = nullptr) {
;     ...
;     for (int p = 0; p < 8; ++p) { const int idx = tid + 512 * p, r = idx >> 6, c4 = idx & 63;
;         v[p] = __builtin_nontemporal_load((const f32x4*)(src + (size_t)(kb * 64 + r) * N + nb * 256 + c4 * 4)); }
.Ltc_advend_68:
	s_cmp_eq_u32 s43, 0
	s_cbranch_scc1 .Ltc_skipB_96
	v_mad_u32_u24 v97, s49, 0, v96
	v_mad_u32_u24 v98, s49, 1, v96
	v_mad_u32_u24 v99, s49, 2, v96
	v_mad_u32_u24 v100, s49, 3, v96
	v_mad_u32_u24 v101, s49, 4, v96
	v_mad_u32_u24 v102, s49, 5, v96
	v_mad_u32_u24 v103, s49, 6, v96
	v_mad_u32_u24 v104, s49, 7, v96
	global_load_dwordx4 v[0:3], v97, s[44:45] nt
	global_load_dwordx4 v[4:7], v98, s[44:45] nt
	global_load_dwordx4 v[8:11], v99, s[44:45] nt
	global_load_dwordx4 v[12:15], v100, s[44:45] nt
	global_load_dwordx4 v[16:19], v101, s[44:45] nt
	global_load_dwordx4 v[20:23], v102, s[44:45] nt
	global_load_dwordx4 v[24:27], v103, s[44:45] nt
	global_load_dwordx4 v[28:31], v104, s[44:45] nt

; __device__ __forceinline__ int tid_fresh() { int t = threadIdx.x; asm volatile("" : "+v"(t)); return t; }
; __device__ __forceinline__ int bid_fresh() { int t = blockIdx.x; asm volatile("" : "+s"(t)); return t; }
; __device__ __forceinline__ unsigned pk2(float lo, float hi) { const hf32x2 v = {lo, hi}; return __builtin_bit_cast(unsigned, __builtin_convertvector(v, hbf16x2)); }
; __device__ __forceinline__ void tconv_tile_w(const float* src, int N, int kb, int nb, bf16_t* dst, int ldd, float* tile, const float* kscale = nullptr) {
;     ...
;     for (int p = 0; p < 8; ++p) { const int idx = tid + 512 * p, r = idx >> 6, c4 = idx & 63;
;         float* t = tile + r * 257 + c4 * 4; t[0] = v[p][0]; t[1] = v[p][1]; t[2] = v[p][2]; t[3] = v[p][3]; }
;     __syncthreads();
; #pragma unroll
;     for (int q = 0; q < 4; ++q) { const int id = tid + 512 * q, n = id >> 3, k8 = id & 7;
;         const float* s = tile + (k8 * 8) * 257 + n;
;         u32x4 o; o.x = pk2(s[0], s[257]); o.y = pk2(s[2 * 257], s[3 * 257]); o.z = pk2(s[4 * 257], s[5 * 257]); o.w = pk2(s[6 * 257], s[7 * 257]);
;         *(u32x4*)(dst + (size_t)(nb * 256 + n) * ldd + kb * 64 + k8 * 8) = o; }
;     __syncthreads();
; }
; __device__ __forceinline__ void phase0(PP p, unsigned char* shm) {
;     ...
;         if (r < C_POOL) { const int gi = r >> 2, q = r & 3; tconv_tile(p->in[15] + (size_t)(l * 4 + gi) * 128 * 128, 128, q >> 1, q & 1, wsm + (size_t)(512 + gi * 128) * 512 + gi * 128, 512, tile); continue; } r -= C_POOL;
;         tconv_tile_w(p->in[21] + (size_t)l * 512 * 512, 512, r / 2, r % 2, wsm + (size_t)1024 * 512, 512, tile);
;     }
;     {
;         const int gt = bid_fresh() * 512 + tid_fresh(), NT = gridDim.x * 512;
;         for (int i = gt; i < DEPTH * 512 * 64; i += NT) {
;             const int l = i / (512 * 64), rr = (i / 64) % 512, ch = i % 64;
;             if ((rr >> 7) != (ch >> 4)) { bf16_t* wsm = (bf16_t*)(ws + WS_WSM) + (size_t)l * 1536 * 512; *(u32x4*)(wsm + (size_t)(512 + rr) * 512 + ch * 8) = (u32x4){0u, 0u, 0u, 0u}; }
.Ltc_wd_98:
	s_mov_b32 s60, 0
	s_cmp_eq_u32 s59, 0
	s_cbranch_scc1 .Ltc_pnosc_100
	v_mul_f32_e32 v32, s68, v32
	v_mul_f32_e32 v33, s68, v33
	v_mul_f32_e32 v34, s68, v34
	v_mul_f32_e32 v35, s68, v35
	v_mul_f32_e32 v36, s69, v36
	v_mul_f32_e32 v37, s69, v37
	v_mul_f32_e32 v38, s69, v38
	v_mul_f32_e32 v39, s69, v39
	v_mul_f32_e32 v40, s70, v40
	v_mul_f32_e32 v41, s70, v41
	v_mul_f32_e32 v42, s70, v42
	v_mul_f32_e32 v43, s70, v43
	v_mul_f32_e32 v44, s71, v44
	v_mul_f32_e32 v45, s71, v45
	v_mul_f32_e32 v46, s71, v46
	v_mul_f32_e32 v47, s71, v47
	v_mul_f32_e32 v48, s72, v48
	v_mul_f32_e32 v49, s72, v49
	v_mul_f32_e32 v50, s72, v50
	v_mul_f32_e32 v51, s72, v51
	v_mul_f32_e32 v52, s73, v52
	v_mul_f32_e32 v53, s73, v53
	v_mul_f32_e32 v54, s73, v54
	v_mul_f32_e32 v55, s73, v55
	v_mul_f32_e32 v56, s74, v56
	v_mul_f32_e32 v57, s74, v57
	v_mul_f32_e32 v58, s74, v58
	v_mul_f32_e32 v59, s74, v59
	v_mul_f32_e32 v60, s75, v60
	v_mul_f32_e32 v61, s75, v61
	v_mul_f32_e32 v62, s75, v62
	v_mul_f32_e32 v63, s75, v63
.Ltc_pnosc_100:
	v_cvt_pk_bf16_f32 v64, v32, v36
	v_cvt_pk_bf16_f32 v65, v33, v37
	v_cvt_pk_bf16_f32 v66, v34, v38
	v_cvt_pk_bf16_f32 v67, v35, v39
	v_cvt_pk_bf16_f32 v68, v40, v44
	v_cvt_pk_bf16_f32 v69, v41, v45
	v_cvt_pk_bf16_f32 v70, v42, v46
	v_cvt_pk_bf16_f32 v71, v43, v47
	v_cvt_pk_bf16_f32 v72, v48, v52
	v_cvt_pk_bf16_f32 v73, v49, v53
	v_cvt_pk_bf16_f32 v74, v50, v54
	v_cvt_pk_bf16_f32 v75, v51, v55
	v_cvt_pk_bf16_f32 v76, v56, v60
	v_cvt_pk_bf16_f32 v77, v57, v61
	v_cvt_pk_bf16_f32 v78, v58, v62
	v_cvt_pk_bf16_f32 v79, v59, v63
	ds_write2_b32 v118, v64, v65 offset1:1
	ds_write2_b32 v118, v66, v67 offset0:2 offset1:3
	ds_write2_b32 v119, v68, v69 offset1:1
	ds_write2_b32 v119, v70, v71 offset0:2 offset1:3
	ds_write2_b32 v120, v72, v73 offset1:1
	ds_write2_b32 v120, v74, v75 offset0:2 offset1:3
	ds_write2_b32 v121, v76, v77 offset1:1
	ds_write2_b32 v121, v78, v79 offset0:2 offset1:3
	v_add_u32_e32 v113, 0, v108
	v_mad_u32_u24 v109, v113, s52, v107
	v_add_u32_e32 v113, 64, v108
	v_mad_u32_u24 v110, v113, s52, v107
	v_add_u32_e32 v113, 128, v108
	v_mad_u32_u24 v111, v113, s52, v107
	v_add_u32_e32 v113, 192, v108
	v_mad_u32_u24 v112, v113, s52, v107
	s_waitcnt lgkmcnt(0)
	s_barrier
	ds_read_b32 v80, v106 offset:33024
	ds_read_b32 v81, v106 offset:34052
	ds_read_b32 v82, v106 offset:35080
	ds_read_b32 v83, v106 offset:36108
	ds_read_b32 v84, v106 offset:33280
	ds_read_b32 v85, v106 offset:34308
	ds_read_b32 v86, v106 offset:35336
	ds_read_b32 v87, v106 offset:36364
	ds_read_b32 v88, v106 offset:33536
	ds_read_b32 v89, v106 offset:34564
	ds_read_b32 v90, v106 offset:35592
	ds_read_b32 v91, v106 offset:36620
	ds_read_b32 v92, v106 offset:33792
	ds_read_b32 v93, v106 offset:34820
	ds_read_b32 v94, v106 offset:35848
	ds_read_b32 v95, v106 offset:36876
	s_waitcnt lgkmcnt(12)
	global_store_dwordx4 v109, v[80:83], s[50:51]
	s_waitcnt lgkmcnt(8)
	global_store_dwordx4 v110, v[84:87], s[50:51]
	s_waitcnt lgkmcnt(4)
	global_store_dwordx4 v111, v[88:91], s[50:51]
	s_waitcnt lgkmcnt(0)
	global_store_dwordx4 v112, v[92:95], s[50:51]
	s_cmp_eq_u32 s43, 0
	s_cbranch_scc1 .Ltc_exit_28
	s_waitcnt lgkmcnt(0)
	s_mov_b64 s[50:51], s[46:47]
	s_mov_b32 s52, s48
	s_mov_b32 s59, s61
	s_mov_b64 s[68:69], s[76:77]
	s_mov_b64 s[70:71], s[78:79]
	s_mov_b64 s[72:73], s[80:81]
	s_mov_b64 s[74:75], s[82:83]
	s_branch .Ltc_loop_27
.Ltc_exit_28:
	s_waitcnt vmcnt(0) lgkmcnt(0)
	s_barrier
	s_cmp_lt_u32 s26, 64
	s_cbranch_scc0 .Ltc_poolend_101
	s_load_dwordx2 s[2:3], s[14:15], 0x78
	s_lshr_b32 s4, s26, 4
	s_bfe_u32 s5, s26, 0x20002
	s_bfe_u32 s6, s26, 0x10001
	s_and_b32 s7, s26, 1
	s_lshl_b32 s18, s4, 2
	s_add_u32 s18, s18, s5
	s_lshl_b32 s18, s18, 16
	s_lshl_b32 s19, s6, 15
	s_add_u32 s18, s18, s19
	s_lshl_b32 s19, s7, 8
	s_add_u32 s18, s18, s19
	v_lshlrev_b32_e32 v0, 8, v107
	v_lshl_add_u32 v0, v108, 2, v0
	s_waitcnt lgkmcnt(0)
	s_add_u32 s2, s2, s18
	s_addc_u32 s3, s3, 0
	global_load_dword v1, v0, s[2:3] offset:0
	global_load_dword v2, v0, s[2:3] offset:512
	global_load_dword v3, v0, s[2:3] offset:1024
	global_load_dword v4, v0, s[2:3] offset:1536
	global_load_dword v5, v0, s[2:3] offset:2048
	global_load_dword v6, v0, s[2:3] offset:2560
	global_load_dword v7, v0, s[2:3] offset:3072
	global_load_dword v8, v0, s[2:3] offset:3584
	s_mul_i32 s18, s4, 0x180000
	s_add_u32 s18, s18, 0x17800000
	s_lshl_b32 s19, s5, 7
	s_lshl_b32 s20, s7, 6
	s_add_u32 s20, s20, s19
	s_add_u32 s20, s20, 0x200
	s_lshl_b32 s20, s20, 10
	s_add_u32 s18, s18, s20
	s_lshl_b32 s19, s5, 8
	s_add_u32 s18, s18, s19
	s_lshl_b32 s19, s6, 7
	s_add_u32 s18, s18, s19
	s_add_u32 s2, s12, s18
	s_addc_u32 s3, s13, 0
	v_lshl_add_u32 v9, v108, 10, v107
	s_waitcnt vmcnt(0)
	v_cvt_pk_bf16_f32 v10, v1, v2
	v_cvt_pk_bf16_f32 v11, v3, v4
	v_cvt_pk_bf16_f32 v12, v5, v6
	v_cvt_pk_bf16_f32 v13, v7, v8
	global_store_dwordx4 v9, v[10:13], s[2:3]
.Ltc_poolend_101:
.LBB0_71:
	v_readlane_b32 s30, v254, 2
	s_mov_b32 s2, s30
	v_mov_b32_e32 v0, v222
	s_load_dword s3, s[16:17], 0x10
	s_load_dword s4, s[16:17], 0x0
	v_lshl_add_u32 v2, s2, 9, v0
	s_waitcnt lgkmcnt(0)
	s_lshr_b32 s2, s3, 16
	s_cmp_lg_u32 s2, 0
	s_cselect_b64 s[2:3], -1, 0
	s_cmp_lg_u64 s[2:3], 0
	s_mov_b32 s2, 0x20000
	s_addc_u32 s18, s4, 0
	v_cmp_gt_i32_e32 vcc, s2, v2
	s_and_saveexec_b64 s[2:3], vcc
	s_cbranch_execz .LBB0_76
	s_lshl_b32 s19, s18, 9
	s_add_u32 s4, s12, 0x17800000
	v_mov_b32_e32 v1, 0
	s_addc_u32 s5, s13, 0
	v_lshlrev_b32_e32 v3, 3, v2
	s_lshl_b32 s20, s18, 12
	s_mov_b64 s[6:7], 0
	s_mov_b32 s21, 0x1ffff
	v_mov_b32_e32 v6, v1
	v_mov_b32_e32 v7, v1
	v_mov_b32_e32 v8, v1
	v_mov_b32_e32 v9, v1
	s_branch .LBB0_74
